# K-projection and L1 in-projection epilogues: eight row-scale loads issued together with counted waits (were one vmcnt(0) ladder step per 16-row group)
# baseline (speedup 1.0000x reference)
; DI unsigned pk2(float lo, float hi) { f32x2 v = {lo, hi}; bf16x2_t b = __builtin_convertvector(v, bf16x2_t); return __builtin_bit_cast(unsigned, b); }
;     DI void operator()(const AccT& acc, const Unit& u, int wr, int wc, int fr, int fq) const {
;         const int row0 = u.pm * 256 + wr * 64 + fr, col0 = u.pn * 256 + wc * 32 + 8 * fq;
; #pragma unroll
;         for (int ai = 0; ai < 2; ++ai)
; #pragma unroll
;             for (int m = 0; m < 4; ++m) { const int t = row0 + ai * 128 + m * 16; const float s = rskv[t];
; #pragma unroll
;                 for (int bj = 0; bj < 2; ++bj) { const int c = col0 + bj * 128, h = c >> 6, d = c & 63;
;                     const f32x4 v0 = acc[ai][bj][m][0] * s, v1 = acc[ai][bj][m][1] * s;
;                     u32x4 w; w.x = pk2(v0[0], v0[1]); w.y = pk2(v0[2], v0[3]); w.z = pk2(v1[0], v1[1]); w.w = pk2(v1[2], v1[3]);
;                     *(u32x4*)(KB + ((size_t)h * S + t) * 96 + d) = w; } }
;     }
.LBB0_629:
	v_lshl_add_u32 v146, s51, 8, v150
	v_ashrrev_i32_e32 v147, 31, v146
	v_lshl_add_u64 v[148:149], v[146:147], 2, s[2:3]
	global_load_dword v200, v[148:149], off
	global_load_dword v202, v[148:149], off offset:64
	global_load_dword v204, v[148:149], off offset:128
	global_load_dword v206, v[148:149], off offset:192
	global_load_dword v208, v[148:149], off offset:512
	global_load_dword v210, v[148:149], off offset:576
	global_load_dword v212, v[148:149], off offset:640
	global_load_dword v214, v[148:149], off offset:704
	s_nop 1
	s_lshl_b32 s6, s52, 8
	s_or_b32 s6, s6, s41
	s_ashr_i32 s6, s6, 6
	s_ashr_i32 s7, s6, 31
	s_or_b32 s20, s6, 2
	s_lshl_b64 s[6:7], s[6:7], 14
	s_ashr_i32 s21, s20, 31
	v_lshl_add_u64 v[162:163], s[6:7], 0, v[146:147]
	s_lshl_b64 s[20:21], s[20:21], 14
	v_mad_u64_u32 v[164:165], s[22:23], v162, s39, v[136:137]
	v_lshl_add_u64 v[166:167], s[20:21], 0, v[146:147]
	v_or_b32_e32 v158, 16, v146
	v_mad_i32_i24 v165, v163, s39, v165
	v_mad_u64_u32 v[162:163], s[22:23], v166, s39, v[136:137]
	v_ashrrev_i32_e32 v159, 31, v158
	v_mad_i32_i24 v163, v167, s39, v163
	v_lshl_add_u64 v[160:161], v[158:159], 2, s[2:3]
	s_and_b64 vcc, exec, s[4:5]
	s_waitcnt vmcnt(7)
	v_pk_mul_f32 v[122:123], v[122:123], v[200:201] op_sel_hi:[1,0]
	v_pk_mul_f32 v[120:121], v[120:121], v[200:201] op_sel_hi:[1,0]
	v_pk_mul_f32 v[126:127], v[126:127], v[200:201] op_sel_hi:[1,0]
	v_pk_mul_f32 v[124:125], v[124:125], v[200:201] op_sel_hi:[1,0]
	v_pk_mul_f32 v[118:119], v[118:119], v[200:201] op_sel_hi:[1,0]
	v_pk_mul_f32 v[116:117], v[116:117], v[200:201] op_sel_hi:[1,0]
	v_pk_mul_f32 v[166:167], v[114:115], v[200:201] op_sel_hi:[1,0]
	v_pk_mul_f32 v[156:157], v[112:113], v[200:201] op_sel_hi:[1,0]
	v_cvt_pk_bf16_f32 v112, v120, v121
	v_cvt_pk_bf16_f32 v113, v122, v123
	v_cvt_pk_bf16_f32 v114, v124, v125
	v_cvt_pk_bf16_f32 v115, v126, v127
	v_cvt_pk_bf16_f32 v116, v116, v117
	v_cvt_pk_bf16_f32 v117, v118, v119
	v_cvt_pk_bf16_f32 v118, v156, v157
	v_cvt_pk_bf16_f32 v119, v166, v167
	global_store_dwordx4 v[164:165], v[112:115], off
	global_store_dwordx4 v[162:163], v[116:119], off
	s_nop 1
	v_lshl_add_u64 v[122:123], s[20:21], 0, v[158:159]
	v_lshl_add_u64 v[118:119], s[6:7], 0, v[158:159]
	v_mad_u64_u32 v[120:121], s[22:23], v118, s39, v[136:137]
	v_or_b32_e32 v114, 32, v146
	v_mad_i32_i24 v121, v119, s39, v121
	v_mad_u64_u32 v[118:119], s[22:23], v122, s39, v[136:137]
	v_ashrrev_i32_e32 v115, 31, v114
	v_mad_i32_i24 v119, v123, s39, v119
	v_lshl_add_u64 v[116:117], v[114:115], 2, s[2:3]
	s_waitcnt vmcnt(8)
	v_pk_mul_f32 v[110:111], v[110:111], v[202:203] op_sel_hi:[1,0]
	v_pk_mul_f32 v[108:109], v[108:109], v[202:203] op_sel_hi:[1,0]
	v_pk_mul_f32 v[106:107], v[106:107], v[202:203] op_sel_hi:[1,0]
	v_pk_mul_f32 v[104:105], v[104:105], v[202:203] op_sel_hi:[1,0]
	v_pk_mul_f32 v[102:103], v[102:103], v[202:203] op_sel_hi:[1,0]
	v_pk_mul_f32 v[100:101], v[100:101], v[202:203] op_sel_hi:[1,0]
	v_pk_mul_f32 v[122:123], v[98:99], v[202:203] op_sel_hi:[1,0]
	v_pk_mul_f32 v[112:113], v[96:97], v[202:203] op_sel_hi:[1,0]
	v_cvt_pk_bf16_f32 v96, v108, v109
	v_cvt_pk_bf16_f32 v97, v110, v111
	v_cvt_pk_bf16_f32 v98, v104, v105
	v_cvt_pk_bf16_f32 v99, v106, v107
	v_cvt_pk_bf16_f32 v100, v100, v101
	v_cvt_pk_bf16_f32 v101, v102, v103
	v_cvt_pk_bf16_f32 v102, v112, v113
	v_cvt_pk_bf16_f32 v103, v122, v123
	global_store_dwordx4 v[120:121], v[96:99], off
	global_store_dwordx4 v[118:119], v[100:103], off
	s_nop 1
	v_lshl_add_u64 v[106:107], s[20:21], 0, v[114:115]
	v_lshl_add_u64 v[102:103], s[6:7], 0, v[114:115]
	v_mad_u64_u32 v[104:105], s[22:23], v102, s39, v[136:137]
	v_or_b32_e32 v98, 48, v146
	v_mad_i32_i24 v105, v103, s39, v105
	v_mad_u64_u32 v[102:103], s[22:23], v106, s39, v[136:137]
	v_ashrrev_i32_e32 v99, 31, v98
	v_mad_i32_i24 v103, v107, s39, v103
	v_lshl_add_u64 v[100:101], v[98:99], 2, s[2:3]
	s_waitcnt vmcnt(9)
	v_pk_mul_f32 v[94:95], v[94:95], v[204:205] op_sel_hi:[1,0]
	v_pk_mul_f32 v[92:93], v[92:93], v[204:205] op_sel_hi:[1,0]
	v_pk_mul_f32 v[90:91], v[90:91], v[204:205] op_sel_hi:[1,0]
	v_pk_mul_f32 v[88:89], v[88:89], v[204:205] op_sel_hi:[1,0]
	v_pk_mul_f32 v[86:87], v[86:87], v[204:205] op_sel_hi:[1,0]
	v_pk_mul_f32 v[84:85], v[84:85], v[204:205] op_sel_hi:[1,0]
	v_pk_mul_f32 v[106:107], v[82:83], v[204:205] op_sel_hi:[1,0]
	v_pk_mul_f32 v[96:97], v[80:81], v[204:205] op_sel_hi:[1,0]
	v_cvt_pk_bf16_f32 v80, v92, v93
	v_cvt_pk_bf16_f32 v81, v94, v95
	v_cvt_pk_bf16_f32 v82, v88, v89
	v_cvt_pk_bf16_f32 v83, v90, v91
	v_cvt_pk_bf16_f32 v84, v84, v85
	v_cvt_pk_bf16_f32 v85, v86, v87
	v_cvt_pk_bf16_f32 v86, v96, v97
	v_cvt_pk_bf16_f32 v87, v106, v107
	global_store_dwordx4 v[104:105], v[80:83], off
	global_store_dwordx4 v[102:103], v[84:87], off
	s_nop 1
	v_lshl_add_u64 v[82:83], s[6:7], 0, v[98:99]
	v_mad_u64_u32 v[84:85], s[22:23], v82, s39, v[136:137]
	v_lshl_add_u64 v[86:87], s[20:21], 0, v[98:99]
	v_mad_i32_i24 v85, v83, s39, v85
	v_mad_u64_u32 v[82:83], s[22:23], v86, s39, v[136:137]
	v_mad_i32_i24 v83, v87, s39, v83
	s_waitcnt vmcnt(10)
; DI unsigned pk2(float lo, float hi) { f32x2 v = {lo, hi}; bf16x2_t b = __builtin_convertvector(v, bf16x2_t); return __builtin_bit_cast(unsigned, b); }
;     DI void operator()(const AccT& acc, const Unit& u, int wr, int wc, int fr, int fq) const {
;     ...
; #pragma unroll
;         for (int ai = 0; ai < 2; ++ai)
; #pragma unroll
;             for (int m = 0; m < 4; ++m) { const int t = row0 + ai * 128 + m * 16; const float s = rskv[t];
; #pragma unroll
;                 for (int bj = 0; bj < 2; ++bj) { const int c = col0 + bj * 128, h = c >> 6, d = c & 63;
;                     const f32x4 v0 = acc[ai][bj][m][0] * s, v1 = acc[ai][bj][m][1] * s;
;                     u32x4 w; w.x = pk2(v0[0], v0[1]); w.y = pk2(v0[2], v0[3]); w.z = pk2(v1[0], v1[1]); w.w = pk2(v1[2], v1[3]);
;                     *(u32x4*)(KB + ((size_t)h * S + t) * 96 + d) = w; } }
;     }
	v_pk_mul_f32 v[78:79], v[78:79], v[206:207] op_sel_hi:[1,0]
	v_pk_mul_f32 v[76:77], v[76:77], v[206:207] op_sel_hi:[1,0]
	v_pk_mul_f32 v[74:75], v[74:75], v[206:207] op_sel_hi:[1,0]
	v_pk_mul_f32 v[72:73], v[72:73], v[206:207] op_sel_hi:[1,0]
	v_pk_mul_f32 v[70:71], v[70:71], v[206:207] op_sel_hi:[1,0]
	v_pk_mul_f32 v[68:69], v[68:69], v[206:207] op_sel_hi:[1,0]
	v_pk_mul_f32 v[86:87], v[66:67], v[206:207] op_sel_hi:[1,0]
	v_pk_mul_f32 v[80:81], v[64:65], v[206:207] op_sel_hi:[1,0]
	v_cvt_pk_bf16_f32 v64, v76, v77
	v_cvt_pk_bf16_f32 v65, v78, v79
	v_cvt_pk_bf16_f32 v66, v72, v73
	v_cvt_pk_bf16_f32 v67, v74, v75
	v_cvt_pk_bf16_f32 v68, v68, v69
	v_cvt_pk_bf16_f32 v69, v70, v71
	v_cvt_pk_bf16_f32 v70, v80, v81
	v_cvt_pk_bf16_f32 v71, v86, v87
	global_store_dwordx4 v[84:85], v[64:67], off
	global_store_dwordx4 v[82:83], v[68:71], off
	s_nop 1
	v_add_u32_e32 v66, 0x80, v146
	v_ashrrev_i32_e32 v67, 31, v66
	v_lshl_add_u64 v[68:69], s[6:7], 0, v[66:67]
	v_mad_u64_u32 v[70:71], s[22:23], v68, s39, v[136:137]
	v_lshl_add_u64 v[66:67], s[20:21], 0, v[66:67]
	v_mad_i32_i24 v71, v69, s39, v71
	v_mad_u64_u32 v[68:69], s[22:23], v66, s39, v[136:137]
	v_mad_i32_i24 v69, v67, s39, v69
	s_waitcnt vmcnt(11)
	v_pk_mul_f32 v[62:63], v[62:63], v[208:209] op_sel_hi:[1,0]
	v_pk_mul_f32 v[60:61], v[60:61], v[208:209] op_sel_hi:[1,0]
	v_pk_mul_f32 v[58:59], v[58:59], v[208:209] op_sel_hi:[1,0]
	v_pk_mul_f32 v[56:57], v[56:57], v[208:209] op_sel_hi:[1,0]
	v_pk_mul_f32 v[54:55], v[54:55], v[208:209] op_sel_hi:[1,0]
	v_pk_mul_f32 v[52:53], v[52:53], v[208:209] op_sel_hi:[1,0]
	v_pk_mul_f32 v[66:67], v[50:51], v[208:209] op_sel_hi:[1,0]
	v_pk_mul_f32 v[64:65], v[48:49], v[208:209] op_sel_hi:[1,0]
	v_cvt_pk_bf16_f32 v48, v60, v61
	v_cvt_pk_bf16_f32 v49, v62, v63
	v_cvt_pk_bf16_f32 v50, v56, v57
	v_cvt_pk_bf16_f32 v51, v58, v59
	v_cvt_pk_bf16_f32 v52, v52, v53
	v_cvt_pk_bf16_f32 v53, v54, v55
	v_cvt_pk_bf16_f32 v54, v64, v65
	v_cvt_pk_bf16_f32 v55, v66, v67
	global_store_dwordx4 v[70:71], v[48:51], off
	global_store_dwordx4 v[68:69], v[52:55], off
	s_nop 1
	v_add_u32_e32 v50, 0x90, v146
	v_ashrrev_i32_e32 v51, 31, v50
	v_lshl_add_u64 v[52:53], s[6:7], 0, v[50:51]
	v_mad_u64_u32 v[54:55], s[22:23], v52, s39, v[136:137]
	v_lshl_add_u64 v[50:51], s[20:21], 0, v[50:51]
	v_mad_i32_i24 v55, v53, s39, v55
	v_mad_u64_u32 v[52:53], s[22:23], v50, s39, v[136:137]
	v_mad_i32_i24 v53, v51, s39, v53
	s_waitcnt vmcnt(12)
	v_pk_mul_f32 v[46:47], v[46:47], v[210:211] op_sel_hi:[1,0]
	v_pk_mul_f32 v[44:45], v[44:45], v[210:211] op_sel_hi:[1,0]
	v_pk_mul_f32 v[42:43], v[42:43], v[210:211] op_sel_hi:[1,0]
	v_pk_mul_f32 v[40:41], v[40:41], v[210:211] op_sel_hi:[1,0]
	v_pk_mul_f32 v[38:39], v[38:39], v[210:211] op_sel_hi:[1,0]
	v_pk_mul_f32 v[36:37], v[36:37], v[210:211] op_sel_hi:[1,0]
	v_pk_mul_f32 v[50:51], v[34:35], v[210:211] op_sel_hi:[1,0]
	v_pk_mul_f32 v[48:49], v[32:33], v[210:211] op_sel_hi:[1,0]
	v_cvt_pk_bf16_f32 v32, v44, v45
	v_cvt_pk_bf16_f32 v33, v46, v47
	v_cvt_pk_bf16_f32 v34, v40, v41
	v_cvt_pk_bf16_f32 v35, v42, v43
	v_cvt_pk_bf16_f32 v36, v36, v37
	v_cvt_pk_bf16_f32 v37, v38, v39
	v_cvt_pk_bf16_f32 v38, v48, v49
	v_cvt_pk_bf16_f32 v39, v50, v51
	global_store_dwordx4 v[54:55], v[32:35], off
	global_store_dwordx4 v[52:53], v[36:39], off
	s_nop 1
	v_add_u32_e32 v34, 0xa0, v146
	v_ashrrev_i32_e32 v35, 31, v34
	v_lshl_add_u64 v[36:37], s[6:7], 0, v[34:35]
	v_mad_u64_u32 v[38:39], s[22:23], v36, s39, v[136:137]
	v_lshl_add_u64 v[34:35], s[20:21], 0, v[34:35]
	v_mad_i32_i24 v39, v37, s39, v39
	v_mad_u64_u32 v[36:37], s[22:23], v34, s39, v[136:137]
	v_mad_i32_i24 v37, v35, s39, v37
	s_waitcnt vmcnt(13)
	v_pk_mul_f32 v[30:31], v[30:31], v[212:213] op_sel_hi:[1,0]
	v_pk_mul_f32 v[28:29], v[28:29], v[212:213] op_sel_hi:[1,0]
	v_pk_mul_f32 v[26:27], v[26:27], v[212:213] op_sel_hi:[1,0]
	v_pk_mul_f32 v[24:25], v[24:25], v[212:213] op_sel_hi:[1,0]
	v_pk_mul_f32 v[22:23], v[22:23], v[212:213] op_sel_hi:[1,0]
	v_pk_mul_f32 v[20:21], v[20:21], v[212:213] op_sel_hi:[1,0]
	v_pk_mul_f32 v[34:35], v[18:19], v[212:213] op_sel_hi:[1,0]
	v_pk_mul_f32 v[32:33], v[16:17], v[212:213] op_sel_hi:[1,0]
	v_cvt_pk_bf16_f32 v16, v28, v29
	v_cvt_pk_bf16_f32 v17, v30, v31
	v_cvt_pk_bf16_f32 v18, v24, v25
	v_cvt_pk_bf16_f32 v19, v26, v27
	v_cvt_pk_bf16_f32 v20, v20, v21
	v_cvt_pk_bf16_f32 v21, v22, v23
	v_cvt_pk_bf16_f32 v22, v32, v33
	v_cvt_pk_bf16_f32 v23, v34, v35
	global_store_dwordx4 v[38:39], v[16:19], off
	global_store_dwordx4 v[36:37], v[20:23], off
	s_nop 1
	v_add_u32_e32 v18, 0xb0, v146
	v_ashrrev_i32_e32 v19, 31, v18
	v_lshl_add_u64 v[20:21], s[6:7], 0, v[18:19]
	v_mad_u64_u32 v[22:23], s[4:5], v20, s39, v[136:137]
	v_lshl_add_u64 v[18:19], s[20:21], 0, v[18:19]
	v_mad_i32_i24 v23, v21, s39, v23
	v_mad_u64_u32 v[20:21], s[4:5], v18, s39, v[136:137]
	v_mad_i32_i24 v21, v19, s39, v21
	s_mov_b64 s[4:5], -1
	s_waitcnt vmcnt(14)
	v_pk_mul_f32 v[14:15], v[14:15], v[214:215] op_sel_hi:[1,0]
	v_pk_mul_f32 v[12:13], v[12:13], v[214:215] op_sel_hi:[1,0]
	v_pk_mul_f32 v[10:11], v[10:11], v[214:215] op_sel_hi:[1,0]
	v_pk_mul_f32 v[8:9], v[8:9], v[214:215] op_sel_hi:[1,0]
	v_pk_mul_f32 v[6:7], v[6:7], v[214:215] op_sel_hi:[1,0]
	v_pk_mul_f32 v[4:5], v[4:5], v[214:215] op_sel_hi:[1,0]
	v_pk_mul_f32 v[18:19], v[2:3], v[214:215] op_sel_hi:[1,0]
	v_pk_mul_f32 v[16:17], v[0:1], v[214:215] op_sel_hi:[1,0]
	v_cvt_pk_bf16_f32 v0, v12, v13
	v_cvt_pk_bf16_f32 v1, v14, v15
	v_cvt_pk_bf16_f32 v2, v8, v9
	v_cvt_pk_bf16_f32 v3, v10, v11
	v_cvt_pk_bf16_f32 v4, v4, v5
	v_cvt_pk_bf16_f32 v5, v6, v7
	v_cvt_pk_bf16_f32 v6, v16, v17
	v_cvt_pk_bf16_f32 v7, v18, v19
	global_store_dwordx4 v[22:23], v[0:3], off
	global_store_dwordx4 v[20:21], v[4:7], off
	s_cbranch_vccnz .LBB0_615
	s_andn2_b64 vcc, exec, s[0:1]
	s_cbranch_vccnz .LBB0_614
	s_barrier
	s_branch .LBB0_614

; DI unsigned pk2(float lo, float hi) { f32x2 v = {lo, hi}; bf16x2_t b = __builtin_convertvector(v, bf16x2_t); return __builtin_bit_cast(unsigned, b); }
; DI float rs_from_ss(u64 ssq) { return rsqrtf((float)ssq * (1.f / (1048576.f * 1024.f)) + EPS); }
;     DI void operator()(const AccT& acc, const Unit& u, int wr, int wc, int fr, int fq) const {
;         const int row0 = u.pm * 256 + wr * 64 + fr, col0 = u.pn * 256 + wc * 32 + 8 * fq;
; #pragma unroll
;         for (int ai = 0; ai < 2; ++ai)
; #pragma unroll
;             for (int m = 0; m < 4; ++m) { const int row = row0 + ai * 128 + m * 16;
;                 const float s = rs_from_ss(((const u64*)sc)[row]);
;                 bf16_t* rowp = O + (size_t)row * 2048 + col0;
; #pragma unroll
;                 for (int bj = 0; bj < 2; ++bj) { const f32x4 v0 = acc[ai][bj][m][0] * s, v1 = acc[ai][bj][m][1] * s;
;                     u32x4 w; w.x = pk2(v0[0], v0[1]); w.y = pk2(v0[2], v0[3]); w.z = pk2(v1[0], v1[1]); w.w = pk2(v1[2], v1[3]);
;                     *(u32x4*)(rowp + bj * 128) = w;
;                     if (u.pn >= 6) { bf16_t* kt = KT + (size_t)(col0 + bj * 128 - 1536) * S + row;
;                         kt[0] = (bf16_t)(w.x & 0xffffu); kt[(size_t)S] = (bf16_t)(w.x >> 16); kt[(size_t)2 * S] = (bf16_t)(w.y & 0xffffu); kt[(size_t)3 * S] = (bf16_t)(w.y >> 16);
;                         kt[(size_t)4 * S] = (bf16_t)(w.z & 0xffffu); kt[(size_t)5 * S] = (bf16_t)(w.z >> 16); kt[(size_t)6 * S] = (bf16_t)(w.w & 0xffffu); kt[(size_t)7 * S] = (bf16_t)(w.w >> 16); } } }
.LBB0_1306:
	v_lshl_add_u32 v144, s10, 8, v156
	v_ashrrev_i32_e32 v145, 31, v144
	v_lshl_add_u64 v[150:151], v[144:145], 3, s[4:5]
	global_load_dwordx2 v[200:201], v[150:151], off
	global_load_dwordx2 v[202:203], v[150:151], off offset:128
	global_load_dwordx2 v[204:205], v[150:151], off offset:256
	global_load_dwordx2 v[206:207], v[150:151], off offset:384
	global_load_dwordx2 v[208:209], v[150:151], off offset:1024
	global_load_dwordx2 v[210:211], v[150:151], off offset:1152
	global_load_dwordx2 v[212:213], v[150:151], off offset:1280
	global_load_dwordx2 v[214:215], v[150:151], off offset:1408
	v_lshl_or_b32 v152, s8, 8, v158
	s_cmp_gt_i32 s8, 5
	v_ashrrev_i32_e32 v153, 31, v152
	s_cselect_b64 s[10:11], -1, 0
	s_cmp_lt_i32 s8, 6
	s_waitcnt vmcnt(7)
	v_ffbh_u32_e32 v148, v201
	v_min_u32_e32 v149, 32, v148
	v_lshlrev_b64 v[146:147], v149, v[200:201]
	v_min_u32_e32 v146, 1, v146
	v_or_b32_e32 v146, v147, v146
	v_cvt_f32_u32_e32 v146, v146
	v_sub_u32_e32 v147, 32, v149
	v_add_u32_e32 v148, 0xfffffa00, v152
	v_ldexp_f32 v146, v146, v147
	v_fmamk_f32 v146, v146, 0x30800000, v162
	v_mul_f32_e32 v147, 0x4b800000, v146
	v_cmp_gt_f32_e32 vcc, s63, v146
	s_nop 1
	v_cndmask_b32_e32 v146, v146, v147, vcc
	v_rsq_f32_e32 v149, v146
	v_lshlrev_b64 v[146:147], 12, v[144:145]
	v_lshl_add_u64 v[146:147], s[2:3], 0, v[146:147]
	v_lshl_add_u64 v[146:147], v[152:153], 1, v[146:147]
	v_mul_f32_e32 v154, 0x45800000, v149
	v_cndmask_b32_e32 v154, v149, v154, vcc
	v_pk_mul_f32 v[126:127], v[126:127], v[154:155] op_sel_hi:[1,0]
	v_pk_mul_f32 v[124:125], v[124:125], v[154:155] op_sel_hi:[1,0]
	v_pk_mul_f32 v[164:165], v[122:123], v[154:155] op_sel_hi:[1,0]
	v_pk_mul_f32 v[122:123], v[120:121], v[154:155] op_sel_hi:[1,0]
	v_cvt_pk_bf16_f32 v120, v124, v125
	v_cvt_pk_bf16_f32 v121, v126, v127
	v_cvt_pk_bf16_f32 v122, v122, v123
	v_cvt_pk_bf16_f32 v123, v164, v165
	v_ashrrev_i32_e32 v149, 31, v148
	global_store_dwordx4 v[146:147], v[120:123], off
	s_cbranch_scc1 .LBB0_1308
	v_lshlrev_b64 v[124:125], 15, v[148:149]
	v_lshl_add_u64 v[124:125], s[12:13], 0, v[124:125]
	v_lshl_add_u64 v[124:125], v[144:145], 1, v[124:125]
	v_add_co_u32_e32 v126, vcc, 0x8000, v124
	global_store_short v[124:125], v120, off
	s_nop 0
	v_addc_co_u32_e32 v127, vcc, 0, v125, vcc
	global_store_short_d16_hi v[126:127], v120, off
	v_add_co_u32_e32 v126, vcc, 0x10000, v124
	s_nop 1
	v_addc_co_u32_e32 v127, vcc, 0, v125, vcc
	global_store_short v[126:127], v121, off
	v_add_co_u32_e32 v126, vcc, 0x18000, v124
	s_nop 1
	v_addc_co_u32_e32 v127, vcc, 0, v125, vcc
	v_add_co_u32_e32 v120, vcc, 0x20000, v124
	global_store_short_d16_hi v[126:127], v121, off
	s_nop 0
	v_addc_co_u32_e32 v121, vcc, 0, v125, vcc
	global_store_short v[120:121], v122, off
	v_add_co_u32_e32 v120, vcc, 0x28000, v124
	s_nop 1
	v_addc_co_u32_e32 v121, vcc, 0, v125, vcc
	global_store_short_d16_hi v[120:121], v122, off
	v_add_co_u32_e32 v120, vcc, 0x30000, v124
	s_nop 1
	v_addc_co_u32_e32 v121, vcc, 0, v125, vcc
	global_store_short v[120:121], v123, off
	v_add_co_u32_e32 v120, vcc, 0x38000, v124
	s_nop 1
	v_addc_co_u32_e32 v121, vcc, 0, v125, vcc
	global_store_short_d16_hi v[120:121], v123, off

; DI unsigned pk2(float lo, float hi) { f32x2 v = {lo, hi}; bf16x2_t b = __builtin_convertvector(v, bf16x2_t); return __builtin_bit_cast(unsigned, b); }
; DI float rs_from_ss(u64 ssq) { return rsqrtf((float)ssq * (1.f / (1048576.f * 1024.f)) + EPS); }
;     DI void operator()(const AccT& acc, const Unit& u, int wr, int wc, int fr, int fq) const {
;     ...
;             for (int m = 0; m < 4; ++m) { const int row = row0 + ai * 128 + m * 16;
;                 const float s = rs_from_ss(((const u64*)sc)[row]);
;                 bf16_t* rowp = O + (size_t)row * 2048 + col0;
; #pragma unroll
;                 for (int bj = 0; bj < 2; ++bj) { const f32x4 v0 = acc[ai][bj][m][0] * s, v1 = acc[ai][bj][m][1] * s;
;                     u32x4 w; w.x = pk2(v0[0], v0[1]); w.y = pk2(v0[2], v0[3]); w.z = pk2(v1[0], v1[1]); w.w = pk2(v1[2], v1[3]);
;                     *(u32x4*)(rowp + bj * 128) = w;
;                     if (u.pn >= 6) { bf16_t* kt = KT + (size_t)(col0 + bj * 128 - 1536) * S + row;
;                         kt[0] = (bf16_t)(w.x & 0xffffu); kt[(size_t)S] = (bf16_t)(w.x >> 16); kt[(size_t)2 * S] = (bf16_t)(w.y & 0xffffu); kt[(size_t)3 * S] = (bf16_t)(w.y >> 16);
;                         kt[(size_t)4 * S] = (bf16_t)(w.z & 0xffffu); kt[(size_t)5 * S] = (bf16_t)(w.z >> 16); kt[(size_t)6 * S] = (bf16_t)(w.w & 0xffffu); kt[(size_t)7 * S] = (bf16_t)(w.w >> 16); } } }
.LBB0_1310:
	s_nop 0
	v_or_b32_e32 v112, 16, v144
	v_ashrrev_i32_e32 v113, 31, v112
	v_lshl_add_u64 v[114:115], v[112:113], 3, s[4:5]
	s_nop 1
	v_lshlrev_b64 v[112:113], 12, v[112:113]
	v_lshl_add_u64 v[112:113], s[2:3], 0, v[112:113]
	v_lshl_add_u64 v[112:113], v[152:153], 1, v[112:113]
	s_waitcnt vmcnt(8)
	v_ffbh_u32_e32 v118, v203
	v_min_u32_e32 v118, 32, v118
	v_lshlrev_b64 v[114:115], v118, v[202:203]
	v_min_u32_e32 v114, 1, v114
	v_or_b32_e32 v114, v115, v114
	v_cvt_f32_u32_e32 v114, v114
	v_sub_u32_e32 v115, 32, v118
	v_ldexp_f32 v114, v114, v115
	v_fmamk_f32 v114, v114, 0x30800000, v162
	v_mul_f32_e32 v115, 0x4b800000, v114
	v_cmp_gt_f32_e32 vcc, s63, v114
	s_nop 1
	v_cndmask_b32_e32 v114, v114, v115, vcc
	v_rsq_f32_e32 v114, v114
	s_nop 0
	v_mul_f32_e32 v115, 0x45800000, v114
	v_cndmask_b32_e32 v114, v114, v115, vcc
	v_pk_mul_f32 v[110:111], v[110:111], v[114:115] op_sel_hi:[1,0]
	v_pk_mul_f32 v[108:109], v[108:109], v[114:115] op_sel_hi:[1,0]
	v_pk_mul_f32 v[118:119], v[106:107], v[114:115] op_sel_hi:[1,0]
	v_pk_mul_f32 v[106:107], v[104:105], v[114:115] op_sel_hi:[1,0]
	v_cvt_pk_bf16_f32 v104, v108, v109
	v_cvt_pk_bf16_f32 v105, v110, v111
	v_cvt_pk_bf16_f32 v106, v106, v107
	v_cvt_pk_bf16_f32 v107, v118, v119
	s_and_b64 vcc, exec, s[8:9]
	global_store_dwordx4 v[112:113], v[104:107], off
	s_cbranch_vccnz .LBB0_1312
	v_lshlrev_b64 v[108:109], 15, v[148:149]
	v_lshl_add_u64 v[108:109], s[12:13], 0, v[108:109]
	v_lshl_add_u64 v[108:109], v[144:145], 1, v[108:109]
	v_add_co_u32_e32 v110, vcc, 0x8000, v108
	global_store_short v[108:109], v104, off offset:32
	s_nop 0
	v_addc_co_u32_e32 v111, vcc, 0, v109, vcc
	global_store_short_d16_hi v[110:111], v104, off offset:32
	v_add_co_u32_e32 v110, vcc, 0x10000, v108
	s_nop 1
	v_addc_co_u32_e32 v111, vcc, 0, v109, vcc
	global_store_short v[110:111], v105, off offset:32
	v_add_co_u32_e32 v110, vcc, 0x18000, v108
	s_nop 1
	v_addc_co_u32_e32 v111, vcc, 0, v109, vcc
	v_add_co_u32_e32 v104, vcc, 0x20000, v108
	global_store_short_d16_hi v[110:111], v105, off offset:32
	s_nop 0
	v_addc_co_u32_e32 v105, vcc, 0, v109, vcc
	global_store_short v[104:105], v106, off offset:32
	v_add_co_u32_e32 v104, vcc, 0x28000, v108
	s_nop 1
	v_addc_co_u32_e32 v105, vcc, 0, v109, vcc
	global_store_short_d16_hi v[104:105], v106, off offset:32
	v_add_co_u32_e32 v104, vcc, 0x30000, v108
	s_nop 1
	v_addc_co_u32_e32 v105, vcc, 0, v109, vcc
	global_store_short v[104:105], v107, off offset:32
	v_add_co_u32_e32 v104, vcc, 0x38000, v108
	s_nop 1
	v_addc_co_u32_e32 v105, vcc, 0, v109, vcc
	global_store_short_d16_hi v[104:105], v107, off offset:32

; DI unsigned pk2(float lo, float hi) { f32x2 v = {lo, hi}; bf16x2_t b = __builtin_convertvector(v, bf16x2_t); return __builtin_bit_cast(unsigned, b); }
; DI float rs_from_ss(u64 ssq) { return rsqrtf((float)ssq * (1.f / (1048576.f * 1024.f)) + EPS); }
;     DI void operator()(const AccT& acc, const Unit& u, int wr, int wc, int fr, int fq) const {
;     ...
;             for (int m = 0; m < 4; ++m) { const int row = row0 + ai * 128 + m * 16;
;                 const float s = rs_from_ss(((const u64*)sc)[row]);
;                 bf16_t* rowp = O + (size_t)row * 2048 + col0;
; #pragma unroll
;                 for (int bj = 0; bj < 2; ++bj) { const f32x4 v0 = acc[ai][bj][m][0] * s, v1 = acc[ai][bj][m][1] * s;
;                     u32x4 w; w.x = pk2(v0[0], v0[1]); w.y = pk2(v0[2], v0[3]); w.z = pk2(v1[0], v1[1]); w.w = pk2(v1[2], v1[3]);
;                     *(u32x4*)(rowp + bj * 128) = w;
;                     if (u.pn >= 6) { bf16_t* kt = KT + (size_t)(col0 + bj * 128 - 1536) * S + row;
;                         kt[0] = (bf16_t)(w.x & 0xffffu); kt[(size_t)S] = (bf16_t)(w.x >> 16); kt[(size_t)2 * S] = (bf16_t)(w.y & 0xffffu); kt[(size_t)3 * S] = (bf16_t)(w.y >> 16);
;                         kt[(size_t)4 * S] = (bf16_t)(w.z & 0xffffu); kt[(size_t)5 * S] = (bf16_t)(w.z >> 16); kt[(size_t)6 * S] = (bf16_t)(w.w & 0xffffu); kt[(size_t)7 * S] = (bf16_t)(w.w >> 16); } } }
.LBB0_1314:
	s_nop 0
	v_or_b32_e32 v96, 32, v144
	v_ashrrev_i32_e32 v97, 31, v96
	v_lshl_add_u64 v[98:99], v[96:97], 3, s[4:5]
	s_nop 1
	v_lshlrev_b64 v[96:97], 12, v[96:97]
	v_lshl_add_u64 v[96:97], s[2:3], 0, v[96:97]
	v_lshl_add_u64 v[96:97], v[152:153], 1, v[96:97]
	s_waitcnt vmcnt(9)
	v_ffbh_u32_e32 v100, v205
	v_min_u32_e32 v100, 32, v100
	v_lshlrev_b64 v[98:99], v100, v[204:205]
	v_min_u32_e32 v98, 1, v98
	v_or_b32_e32 v98, v99, v98
	v_cvt_f32_u32_e32 v98, v98
	v_sub_u32_e32 v99, 32, v100
	v_ldexp_f32 v98, v98, v99
	v_fmamk_f32 v98, v98, 0x30800000, v162
	v_mul_f32_e32 v99, 0x4b800000, v98
	v_cmp_gt_f32_e32 vcc, s63, v98
	s_nop 1
	v_cndmask_b32_e32 v98, v98, v99, vcc
	v_rsq_f32_e32 v98, v98
	s_nop 0
	v_mul_f32_e32 v99, 0x45800000, v98
	v_cndmask_b32_e32 v98, v98, v99, vcc
	v_pk_mul_f32 v[94:95], v[94:95], v[98:99] op_sel_hi:[1,0]
	v_pk_mul_f32 v[92:93], v[92:93], v[98:99] op_sel_hi:[1,0]
	v_pk_mul_f32 v[100:101], v[90:91], v[98:99] op_sel_hi:[1,0]
	v_pk_mul_f32 v[90:91], v[88:89], v[98:99] op_sel_hi:[1,0]
	v_cvt_pk_bf16_f32 v88, v92, v93
	v_cvt_pk_bf16_f32 v89, v94, v95
	v_cvt_pk_bf16_f32 v90, v90, v91
	v_cvt_pk_bf16_f32 v91, v100, v101
	s_and_b64 vcc, exec, s[8:9]
	global_store_dwordx4 v[96:97], v[88:91], off
	s_cbranch_vccnz .LBB0_1316
	v_lshlrev_b64 v[92:93], 15, v[148:149]
	v_lshl_add_u64 v[92:93], s[12:13], 0, v[92:93]
	v_lshl_add_u64 v[92:93], v[144:145], 1, v[92:93]
	v_add_co_u32_e32 v94, vcc, 0x8000, v92
	global_store_short v[92:93], v88, off offset:64
	s_nop 0
	v_addc_co_u32_e32 v95, vcc, 0, v93, vcc
	global_store_short_d16_hi v[94:95], v88, off offset:64
	v_add_co_u32_e32 v94, vcc, 0x10000, v92
	s_nop 1
	v_addc_co_u32_e32 v95, vcc, 0, v93, vcc
	global_store_short v[94:95], v89, off offset:64
	v_add_co_u32_e32 v94, vcc, 0x18000, v92
	s_nop 1
	v_addc_co_u32_e32 v95, vcc, 0, v93, vcc
	v_add_co_u32_e32 v88, vcc, 0x20000, v92
	global_store_short_d16_hi v[94:95], v89, off offset:64
	s_nop 0
	v_addc_co_u32_e32 v89, vcc, 0, v93, vcc
	global_store_short v[88:89], v90, off offset:64
	v_add_co_u32_e32 v88, vcc, 0x28000, v92
	s_nop 1
	v_addc_co_u32_e32 v89, vcc, 0, v93, vcc
	global_store_short_d16_hi v[88:89], v90, off offset:64
	v_add_co_u32_e32 v88, vcc, 0x30000, v92
	s_nop 1
	v_addc_co_u32_e32 v89, vcc, 0, v93, vcc
	global_store_short v[88:89], v91, off offset:64
	v_add_co_u32_e32 v88, vcc, 0x38000, v92
	s_nop 1
	v_addc_co_u32_e32 v89, vcc, 0, v93, vcc
	global_store_short_d16_hi v[88:89], v91, off offset:64

; DI unsigned pk2(float lo, float hi) { f32x2 v = {lo, hi}; bf16x2_t b = __builtin_convertvector(v, bf16x2_t); return __builtin_bit_cast(unsigned, b); }
; DI float rs_from_ss(u64 ssq) { return rsqrtf((float)ssq * (1.f / (1048576.f * 1024.f)) + EPS); }
;     DI void operator()(const AccT& acc, const Unit& u, int wr, int wc, int fr, int fq) const {
;     ...
;             for (int m = 0; m < 4; ++m) { const int row = row0 + ai * 128 + m * 16;
;                 const float s = rs_from_ss(((const u64*)sc)[row]);
;                 bf16_t* rowp = O + (size_t)row * 2048 + col0;
; #pragma unroll
;                 for (int bj = 0; bj < 2; ++bj) { const f32x4 v0 = acc[ai][bj][m][0] * s, v1 = acc[ai][bj][m][1] * s;
;                     u32x4 w; w.x = pk2(v0[0], v0[1]); w.y = pk2(v0[2], v0[3]); w.z = pk2(v1[0], v1[1]); w.w = pk2(v1[2], v1[3]);
;                     *(u32x4*)(rowp + bj * 128) = w;
;                     if (u.pn >= 6) { bf16_t* kt = KT + (size_t)(col0 + bj * 128 - 1536) * S + row;
;                         kt[0] = (bf16_t)(w.x & 0xffffu); kt[(size_t)S] = (bf16_t)(w.x >> 16); kt[(size_t)2 * S] = (bf16_t)(w.y & 0xffffu); kt[(size_t)3 * S] = (bf16_t)(w.y >> 16);
;                         kt[(size_t)4 * S] = (bf16_t)(w.z & 0xffffu); kt[(size_t)5 * S] = (bf16_t)(w.z >> 16); kt[(size_t)6 * S] = (bf16_t)(w.w & 0xffffu); kt[(size_t)7 * S] = (bf16_t)(w.w >> 16); } } }
.LBB0_1318:
	s_nop 0
	v_or_b32_e32 v80, 48, v144
	v_ashrrev_i32_e32 v81, 31, v80
	v_lshl_add_u64 v[82:83], v[80:81], 3, s[4:5]
	s_nop 1
	v_lshlrev_b64 v[80:81], 12, v[80:81]
	v_lshl_add_u64 v[80:81], s[2:3], 0, v[80:81]
	v_lshl_add_u64 v[80:81], v[152:153], 1, v[80:81]
	s_waitcnt vmcnt(10)
	v_ffbh_u32_e32 v84, v207
	v_min_u32_e32 v84, 32, v84
	v_lshlrev_b64 v[82:83], v84, v[206:207]
	v_min_u32_e32 v82, 1, v82
	v_or_b32_e32 v82, v83, v82
	v_cvt_f32_u32_e32 v82, v82
	v_sub_u32_e32 v83, 32, v84
	v_ldexp_f32 v82, v82, v83
	v_fmamk_f32 v82, v82, 0x30800000, v162
	v_mul_f32_e32 v83, 0x4b800000, v82
	v_cmp_gt_f32_e32 vcc, s63, v82
	s_nop 1
	v_cndmask_b32_e32 v82, v82, v83, vcc
	v_rsq_f32_e32 v82, v82
	s_nop 0
	v_mul_f32_e32 v83, 0x45800000, v82
	v_cndmask_b32_e32 v82, v82, v83, vcc
	v_pk_mul_f32 v[78:79], v[78:79], v[82:83] op_sel_hi:[1,0]
	v_pk_mul_f32 v[76:77], v[76:77], v[82:83] op_sel_hi:[1,0]
	v_pk_mul_f32 v[84:85], v[74:75], v[82:83] op_sel_hi:[1,0]
	v_pk_mul_f32 v[74:75], v[72:73], v[82:83] op_sel_hi:[1,0]
	v_cvt_pk_bf16_f32 v72, v76, v77
	v_cvt_pk_bf16_f32 v73, v78, v79
	v_cvt_pk_bf16_f32 v74, v74, v75
	v_cvt_pk_bf16_f32 v75, v84, v85
	s_and_b64 vcc, exec, s[8:9]
	global_store_dwordx4 v[80:81], v[72:75], off
	s_cbranch_vccnz .LBB0_1320
	v_lshlrev_b64 v[76:77], 15, v[148:149]
	v_lshl_add_u64 v[76:77], s[12:13], 0, v[76:77]
	v_lshl_add_u64 v[76:77], v[144:145], 1, v[76:77]
	v_add_co_u32_e32 v78, vcc, 0x8000, v76
	global_store_short v[76:77], v72, off offset:96
	s_nop 0
	v_addc_co_u32_e32 v79, vcc, 0, v77, vcc
	global_store_short_d16_hi v[78:79], v72, off offset:96
	v_add_co_u32_e32 v78, vcc, 0x10000, v76
	s_nop 1
	v_addc_co_u32_e32 v79, vcc, 0, v77, vcc
	global_store_short v[78:79], v73, off offset:96
	v_add_co_u32_e32 v78, vcc, 0x18000, v76
	s_nop 1
	v_addc_co_u32_e32 v79, vcc, 0, v77, vcc
	v_add_co_u32_e32 v72, vcc, 0x20000, v76
	global_store_short_d16_hi v[78:79], v73, off offset:96
	s_nop 0
	v_addc_co_u32_e32 v73, vcc, 0, v77, vcc
	global_store_short v[72:73], v74, off offset:96
	v_add_co_u32_e32 v72, vcc, 0x28000, v76
	s_nop 1
	v_addc_co_u32_e32 v73, vcc, 0, v77, vcc
	global_store_short_d16_hi v[72:73], v74, off offset:96
	v_add_co_u32_e32 v72, vcc, 0x30000, v76
	s_nop 1
	v_addc_co_u32_e32 v73, vcc, 0, v77, vcc
	global_store_short v[72:73], v75, off offset:96
	v_add_co_u32_e32 v72, vcc, 0x38000, v76
	s_nop 1
	v_addc_co_u32_e32 v73, vcc, 0, v77, vcc
	global_store_short_d16_hi v[72:73], v75, off offset:96

; DI unsigned pk2(float lo, float hi) { f32x2 v = {lo, hi}; bf16x2_t b = __builtin_convertvector(v, bf16x2_t); return __builtin_bit_cast(unsigned, b); }
; DI float rs_from_ss(u64 ssq) { return rsqrtf((float)ssq * (1.f / (1048576.f * 1024.f)) + EPS); }
;     DI void operator()(const AccT& acc, const Unit& u, int wr, int wc, int fr, int fq) const {
;     ...
;             for (int m = 0; m < 4; ++m) { const int row = row0 + ai * 128 + m * 16;
;                 const float s = rs_from_ss(((const u64*)sc)[row]);
;                 bf16_t* rowp = O + (size_t)row * 2048 + col0;
; #pragma unroll
;                 for (int bj = 0; bj < 2; ++bj) { const f32x4 v0 = acc[ai][bj][m][0] * s, v1 = acc[ai][bj][m][1] * s;
;                     u32x4 w; w.x = pk2(v0[0], v0[1]); w.y = pk2(v0[2], v0[3]); w.z = pk2(v1[0], v1[1]); w.w = pk2(v1[2], v1[3]);
;                     *(u32x4*)(rowp + bj * 128) = w;
;                     if (u.pn >= 6) { bf16_t* kt = KT + (size_t)(col0 + bj * 128 - 1536) * S + row;
;                         kt[0] = (bf16_t)(w.x & 0xffffu); kt[(size_t)S] = (bf16_t)(w.x >> 16); kt[(size_t)2 * S] = (bf16_t)(w.y & 0xffffu); kt[(size_t)3 * S] = (bf16_t)(w.y >> 16);
;                         kt[(size_t)4 * S] = (bf16_t)(w.z & 0xffffu); kt[(size_t)5 * S] = (bf16_t)(w.z >> 16); kt[(size_t)6 * S] = (bf16_t)(w.w & 0xffffu); kt[(size_t)7 * S] = (bf16_t)(w.w >> 16); } } }
.LBB0_1322:
	s_nop 1
	s_waitcnt vmcnt(11)
	v_ffbh_u32_e32 v66, v209
	v_min_u32_e32 v67, 32, v66
	v_lshlrev_b64 v[64:65], v67, v[208:209]
	v_min_u32_e32 v64, 1, v64
	v_or_b32_e32 v64, v65, v64
	v_cvt_f32_u32_e32 v64, v64
	v_sub_u32_e32 v65, 32, v67
	v_add_co_u32_e32 v66, vcc, 0x80000, v146
	v_ldexp_f32 v64, v64, v65
	v_fmamk_f32 v64, v64, 0x30800000, v162
	v_mul_f32_e32 v65, 0x4b800000, v64
	v_cmp_gt_f32_e64 s[10:11], s63, v64
	v_addc_co_u32_e32 v67, vcc, 0, v147, vcc
	s_nop 0
	v_cndmask_b32_e64 v64, v64, v65, s[10:11]
	v_rsq_f32_e32 v64, v64
	s_and_b64 vcc, exec, s[8:9]
	v_mul_f32_e32 v65, 0x45800000, v64
	v_cndmask_b32_e64 v64, v64, v65, s[10:11]
	v_pk_mul_f32 v[62:63], v[62:63], v[64:65] op_sel_hi:[1,0]
	v_pk_mul_f32 v[60:61], v[60:61], v[64:65] op_sel_hi:[1,0]
	v_pk_mul_f32 v[68:69], v[58:59], v[64:65] op_sel_hi:[1,0]
	v_pk_mul_f32 v[58:59], v[56:57], v[64:65] op_sel_hi:[1,0]
	v_cvt_pk_bf16_f32 v56, v60, v61
	v_cvt_pk_bf16_f32 v57, v62, v63
	v_cvt_pk_bf16_f32 v58, v58, v59
	v_cvt_pk_bf16_f32 v59, v68, v69
	global_store_dwordx4 v[66:67], v[56:59], off
	s_cbranch_vccnz .LBB0_1324
	v_lshlrev_b64 v[60:61], 15, v[148:149]
	v_lshl_add_u64 v[60:61], s[12:13], 0, v[60:61]
	v_lshl_add_u64 v[60:61], v[144:145], 1, v[60:61]
	v_add_co_u32_e32 v62, vcc, 0x8000, v60
	global_store_short v[60:61], v56, off offset:256
	s_nop 0
	v_addc_co_u32_e32 v63, vcc, 0, v61, vcc
	global_store_short_d16_hi v[62:63], v56, off offset:256
	v_add_co_u32_e32 v62, vcc, 0x10000, v60
	s_nop 1
	v_addc_co_u32_e32 v63, vcc, 0, v61, vcc
	global_store_short v[62:63], v57, off offset:256
	v_add_co_u32_e32 v62, vcc, 0x18000, v60
	s_nop 1
	v_addc_co_u32_e32 v63, vcc, 0, v61, vcc
	v_add_co_u32_e32 v56, vcc, 0x20000, v60
	global_store_short_d16_hi v[62:63], v57, off offset:256
	s_nop 0
	v_addc_co_u32_e32 v57, vcc, 0, v61, vcc
	global_store_short v[56:57], v58, off offset:256
	v_add_co_u32_e32 v56, vcc, 0x28000, v60
	s_nop 1
	v_addc_co_u32_e32 v57, vcc, 0, v61, vcc
	global_store_short_d16_hi v[56:57], v58, off offset:256
	v_add_co_u32_e32 v56, vcc, 0x30000, v60
	s_nop 1
	v_addc_co_u32_e32 v57, vcc, 0, v61, vcc
	global_store_short v[56:57], v59, off offset:256
	v_add_co_u32_e32 v56, vcc, 0x38000, v60
	s_nop 1
	v_addc_co_u32_e32 v57, vcc, 0, v61, vcc
	global_store_short_d16_hi v[56:57], v59, off offset:256

; DI unsigned pk2(float lo, float hi) { f32x2 v = {lo, hi}; bf16x2_t b = __builtin_convertvector(v, bf16x2_t); return __builtin_bit_cast(unsigned, b); }
; DI float rs_from_ss(u64 ssq) { return rsqrtf((float)ssq * (1.f / (1048576.f * 1024.f)) + EPS); }
;     DI void operator()(const AccT& acc, const Unit& u, int wr, int wc, int fr, int fq) const {
;     ...
;             for (int m = 0; m < 4; ++m) { const int row = row0 + ai * 128 + m * 16;
;                 const float s = rs_from_ss(((const u64*)sc)[row]);
;                 bf16_t* rowp = O + (size_t)row * 2048 + col0;
; #pragma unroll
;                 for (int bj = 0; bj < 2; ++bj) { const f32x4 v0 = acc[ai][bj][m][0] * s, v1 = acc[ai][bj][m][1] * s;
;                     u32x4 w; w.x = pk2(v0[0], v0[1]); w.y = pk2(v0[2], v0[3]); w.z = pk2(v1[0], v1[1]); w.w = pk2(v1[2], v1[3]);
;                     *(u32x4*)(rowp + bj * 128) = w;
;                     if (u.pn >= 6) { bf16_t* kt = KT + (size_t)(col0 + bj * 128 - 1536) * S + row;
;                         kt[0] = (bf16_t)(w.x & 0xffffu); kt[(size_t)S] = (bf16_t)(w.x >> 16); kt[(size_t)2 * S] = (bf16_t)(w.y & 0xffffu); kt[(size_t)3 * S] = (bf16_t)(w.y >> 16);
;                         kt[(size_t)4 * S] = (bf16_t)(w.z & 0xffffu); kt[(size_t)5 * S] = (bf16_t)(w.z >> 16); kt[(size_t)6 * S] = (bf16_t)(w.w & 0xffffu); kt[(size_t)7 * S] = (bf16_t)(w.w >> 16); } } }
.LBB0_1326:
	s_nop 1
	s_waitcnt vmcnt(12)
	v_ffbh_u32_e32 v50, v211
	v_min_u32_e32 v51, 32, v50
	v_lshlrev_b64 v[48:49], v51, v[210:211]
	v_min_u32_e32 v48, 1, v48
	v_or_b32_e32 v48, v49, v48
	v_cvt_f32_u32_e32 v48, v48
	v_sub_u32_e32 v49, 32, v51
	v_add_co_u32_e32 v50, vcc, 0x90000, v146
	v_ldexp_f32 v48, v48, v49
	v_fmamk_f32 v48, v48, 0x30800000, v162
	v_mul_f32_e32 v49, 0x4b800000, v48
	v_cmp_gt_f32_e64 s[10:11], s63, v48
	v_addc_co_u32_e32 v51, vcc, 0, v147, vcc
	s_nop 0
	v_cndmask_b32_e64 v48, v48, v49, s[10:11]
	v_rsq_f32_e32 v48, v48
	s_and_b64 vcc, exec, s[8:9]
	v_mul_f32_e32 v49, 0x45800000, v48
	v_cndmask_b32_e64 v48, v48, v49, s[10:11]
	v_pk_mul_f32 v[46:47], v[46:47], v[48:49] op_sel_hi:[1,0]
	v_pk_mul_f32 v[44:45], v[44:45], v[48:49] op_sel_hi:[1,0]
	v_pk_mul_f32 v[52:53], v[42:43], v[48:49] op_sel_hi:[1,0]
	v_pk_mul_f32 v[42:43], v[40:41], v[48:49] op_sel_hi:[1,0]
	v_cvt_pk_bf16_f32 v40, v44, v45
	v_cvt_pk_bf16_f32 v41, v46, v47
	v_cvt_pk_bf16_f32 v42, v42, v43
	v_cvt_pk_bf16_f32 v43, v52, v53
	global_store_dwordx4 v[50:51], v[40:43], off
	s_cbranch_vccnz .LBB0_1328
	v_lshlrev_b64 v[44:45], 15, v[148:149]
	v_lshl_add_u64 v[44:45], s[12:13], 0, v[44:45]
	v_lshl_add_u64 v[44:45], v[144:145], 1, v[44:45]
	v_add_co_u32_e32 v46, vcc, 0x8000, v44
	global_store_short v[44:45], v40, off offset:288
	s_nop 0
	v_addc_co_u32_e32 v47, vcc, 0, v45, vcc
	global_store_short_d16_hi v[46:47], v40, off offset:288
	v_add_co_u32_e32 v46, vcc, 0x10000, v44
	s_nop 1
	v_addc_co_u32_e32 v47, vcc, 0, v45, vcc
	global_store_short v[46:47], v41, off offset:288
	v_add_co_u32_e32 v46, vcc, 0x18000, v44
	s_nop 1
	v_addc_co_u32_e32 v47, vcc, 0, v45, vcc
	v_add_co_u32_e32 v40, vcc, 0x20000, v44
	global_store_short_d16_hi v[46:47], v41, off offset:288
	s_nop 0
	v_addc_co_u32_e32 v41, vcc, 0, v45, vcc
	global_store_short v[40:41], v42, off offset:288
	v_add_co_u32_e32 v40, vcc, 0x28000, v44
	s_nop 1
	v_addc_co_u32_e32 v41, vcc, 0, v45, vcc
	global_store_short_d16_hi v[40:41], v42, off offset:288
	v_add_co_u32_e32 v40, vcc, 0x30000, v44
	s_nop 1
	v_addc_co_u32_e32 v41, vcc, 0, v45, vcc
	global_store_short v[40:41], v43, off offset:288
	v_add_co_u32_e32 v40, vcc, 0x38000, v44
	s_nop 1
	v_addc_co_u32_e32 v41, vcc, 0, v45, vcc
	global_store_short_d16_hi v[40:41], v43, off offset:288

; DI unsigned pk2(float lo, float hi) { f32x2 v = {lo, hi}; bf16x2_t b = __builtin_convertvector(v, bf16x2_t); return __builtin_bit_cast(unsigned, b); }
; DI float rs_from_ss(u64 ssq) { return rsqrtf((float)ssq * (1.f / (1048576.f * 1024.f)) + EPS); }
;     DI void operator()(const AccT& acc, const Unit& u, int wr, int wc, int fr, int fq) const {
;     ...
;             for (int m = 0; m < 4; ++m) { const int row = row0 + ai * 128 + m * 16;
;                 const float s = rs_from_ss(((const u64*)sc)[row]);
;                 bf16_t* rowp = O + (size_t)row * 2048 + col0;
; #pragma unroll
;                 for (int bj = 0; bj < 2; ++bj) { const f32x4 v0 = acc[ai][bj][m][0] * s, v1 = acc[ai][bj][m][1] * s;
;                     u32x4 w; w.x = pk2(v0[0], v0[1]); w.y = pk2(v0[2], v0[3]); w.z = pk2(v1[0], v1[1]); w.w = pk2(v1[2], v1[3]);
;                     *(u32x4*)(rowp + bj * 128) = w;
;                     if (u.pn >= 6) { bf16_t* kt = KT + (size_t)(col0 + bj * 128 - 1536) * S + row;
;                         kt[0] = (bf16_t)(w.x & 0xffffu); kt[(size_t)S] = (bf16_t)(w.x >> 16); kt[(size_t)2 * S] = (bf16_t)(w.y & 0xffffu); kt[(size_t)3 * S] = (bf16_t)(w.y >> 16);
;                         kt[(size_t)4 * S] = (bf16_t)(w.z & 0xffffu); kt[(size_t)5 * S] = (bf16_t)(w.z >> 16); kt[(size_t)6 * S] = (bf16_t)(w.w & 0xffffu); kt[(size_t)7 * S] = (bf16_t)(w.w >> 16); } } }
.LBB0_1330:
	s_nop 1
	s_waitcnt vmcnt(13)
	v_ffbh_u32_e32 v34, v213
	v_min_u32_e32 v35, 32, v34
	v_lshlrev_b64 v[32:33], v35, v[212:213]
	v_min_u32_e32 v32, 1, v32
	v_or_b32_e32 v32, v33, v32
	v_cvt_f32_u32_e32 v32, v32
	v_sub_u32_e32 v33, 32, v35
	v_add_co_u32_e32 v34, vcc, 0xa0000, v146
	v_ldexp_f32 v32, v32, v33
	v_fmamk_f32 v32, v32, 0x30800000, v162
	v_mul_f32_e32 v33, 0x4b800000, v32
	v_cmp_gt_f32_e64 s[10:11], s63, v32
	v_addc_co_u32_e32 v35, vcc, 0, v147, vcc
	s_nop 0
	v_cndmask_b32_e64 v32, v32, v33, s[10:11]
	v_rsq_f32_e32 v32, v32
	s_and_b64 vcc, exec, s[8:9]
	v_mul_f32_e32 v33, 0x45800000, v32
	v_cndmask_b32_e64 v32, v32, v33, s[10:11]
	v_pk_mul_f32 v[30:31], v[30:31], v[32:33] op_sel_hi:[1,0]
	v_pk_mul_f32 v[28:29], v[28:29], v[32:33] op_sel_hi:[1,0]
	v_pk_mul_f32 v[36:37], v[26:27], v[32:33] op_sel_hi:[1,0]
	v_pk_mul_f32 v[26:27], v[24:25], v[32:33] op_sel_hi:[1,0]
	v_cvt_pk_bf16_f32 v24, v28, v29
	v_cvt_pk_bf16_f32 v25, v30, v31
	v_cvt_pk_bf16_f32 v26, v26, v27
	v_cvt_pk_bf16_f32 v27, v36, v37
	global_store_dwordx4 v[34:35], v[24:27], off
	s_cbranch_vccnz .LBB0_1332
	v_lshlrev_b64 v[28:29], 15, v[148:149]
	v_lshl_add_u64 v[28:29], s[12:13], 0, v[28:29]
	v_lshl_add_u64 v[28:29], v[144:145], 1, v[28:29]
	v_add_co_u32_e32 v30, vcc, 0x8000, v28
	global_store_short v[28:29], v24, off offset:320
	s_nop 0
	v_addc_co_u32_e32 v31, vcc, 0, v29, vcc
	global_store_short_d16_hi v[30:31], v24, off offset:320
	v_add_co_u32_e32 v30, vcc, 0x10000, v28
	s_nop 1
	v_addc_co_u32_e32 v31, vcc, 0, v29, vcc
	global_store_short v[30:31], v25, off offset:320
	v_add_co_u32_e32 v30, vcc, 0x18000, v28
	s_nop 1
	v_addc_co_u32_e32 v31, vcc, 0, v29, vcc
	v_add_co_u32_e32 v24, vcc, 0x20000, v28
	global_store_short_d16_hi v[30:31], v25, off offset:320
	s_nop 0
	v_addc_co_u32_e32 v25, vcc, 0, v29, vcc
	global_store_short v[24:25], v26, off offset:320
	v_add_co_u32_e32 v24, vcc, 0x28000, v28
	s_nop 1
	v_addc_co_u32_e32 v25, vcc, 0, v29, vcc
	global_store_short_d16_hi v[24:25], v26, off offset:320
	v_add_co_u32_e32 v24, vcc, 0x30000, v28
	s_nop 1
	v_addc_co_u32_e32 v25, vcc, 0, v29, vcc
	global_store_short v[24:25], v27, off offset:320
	v_add_co_u32_e32 v24, vcc, 0x38000, v28
	s_nop 1
	v_addc_co_u32_e32 v25, vcc, 0, v29, vcc
	global_store_short_d16_hi v[24:25], v27, off offset:320

; DI unsigned pk2(float lo, float hi) { f32x2 v = {lo, hi}; bf16x2_t b = __builtin_convertvector(v, bf16x2_t); return __builtin_bit_cast(unsigned, b); }
; DI float rs_from_ss(u64 ssq) { return rsqrtf((float)ssq * (1.f / (1048576.f * 1024.f)) + EPS); }
;     DI void operator()(const AccT& acc, const Unit& u, int wr, int wc, int fr, int fq) const {
;     ...
;             for (int m = 0; m < 4; ++m) { const int row = row0 + ai * 128 + m * 16;
;                 const float s = rs_from_ss(((const u64*)sc)[row]);
;                 bf16_t* rowp = O + (size_t)row * 2048 + col0;
; #pragma unroll
;                 for (int bj = 0; bj < 2; ++bj) { const f32x4 v0 = acc[ai][bj][m][0] * s, v1 = acc[ai][bj][m][1] * s;
;                     u32x4 w; w.x = pk2(v0[0], v0[1]); w.y = pk2(v0[2], v0[3]); w.z = pk2(v1[0], v1[1]); w.w = pk2(v1[2], v1[3]);
;                     *(u32x4*)(rowp + bj * 128) = w;
;                     if (u.pn >= 6) { bf16_t* kt = KT + (size_t)(col0 + bj * 128 - 1536) * S + row;
;                         kt[0] = (bf16_t)(w.x & 0xffffu); kt[(size_t)S] = (bf16_t)(w.x >> 16); kt[(size_t)2 * S] = (bf16_t)(w.y & 0xffffu); kt[(size_t)3 * S] = (bf16_t)(w.y >> 16);
;                         kt[(size_t)4 * S] = (bf16_t)(w.z & 0xffffu); kt[(size_t)5 * S] = (bf16_t)(w.z >> 16); kt[(size_t)6 * S] = (bf16_t)(w.w & 0xffffu); kt[(size_t)7 * S] = (bf16_t)(w.w >> 16); } } }
.LBB0_1334:
	s_nop 1
	s_waitcnt vmcnt(14)
	v_ffbh_u32_e32 v18, v215
	v_min_u32_e32 v19, 32, v18
	v_lshlrev_b64 v[16:17], v19, v[214:215]
	v_min_u32_e32 v16, 1, v16
	v_or_b32_e32 v16, v17, v16
	v_cvt_f32_u32_e32 v16, v16
	v_sub_u32_e32 v17, 32, v19
	v_add_co_u32_e32 v18, vcc, 0xb0000, v146
	v_ldexp_f32 v16, v16, v17
	v_fmamk_f32 v16, v16, 0x30800000, v162
	v_mul_f32_e32 v17, 0x4b800000, v16
	v_cmp_gt_f32_e64 s[10:11], s63, v16
	v_addc_co_u32_e32 v19, vcc, 0, v147, vcc
	s_nop 0
	v_cndmask_b32_e64 v16, v16, v17, s[10:11]
	v_rsq_f32_e32 v16, v16
	s_and_b64 vcc, exec, s[8:9]
	v_mul_f32_e32 v17, 0x45800000, v16
	v_cndmask_b32_e64 v16, v16, v17, s[10:11]
	v_pk_mul_f32 v[14:15], v[14:15], v[16:17] op_sel_hi:[1,0]
	v_pk_mul_f32 v[12:13], v[12:13], v[16:17] op_sel_hi:[1,0]
	v_pk_mul_f32 v[20:21], v[10:11], v[16:17] op_sel_hi:[1,0]
	v_pk_mul_f32 v[10:11], v[8:9], v[16:17] op_sel_hi:[1,0]
	v_cvt_pk_bf16_f32 v8, v12, v13
	v_cvt_pk_bf16_f32 v9, v14, v15
	v_cvt_pk_bf16_f32 v10, v10, v11
	v_cvt_pk_bf16_f32 v11, v20, v21
	global_store_dwordx4 v[18:19], v[8:11], off
	s_cbranch_vccnz .LBB0_1336
	v_lshlrev_b64 v[12:13], 15, v[148:149]
	v_lshl_add_u64 v[12:13], s[12:13], 0, v[12:13]
	v_lshl_add_u64 v[12:13], v[144:145], 1, v[12:13]
	v_add_co_u32_e32 v14, vcc, 0x8000, v12
	global_store_short v[12:13], v8, off offset:352
	s_nop 0
	v_addc_co_u32_e32 v15, vcc, 0, v13, vcc
	global_store_short_d16_hi v[14:15], v8, off offset:352
	v_add_co_u32_e32 v14, vcc, 0x10000, v12
	s_nop 1
	v_addc_co_u32_e32 v15, vcc, 0, v13, vcc
	global_store_short v[14:15], v9, off offset:352
	v_add_co_u32_e32 v14, vcc, 0x18000, v12
	s_nop 1
	v_addc_co_u32_e32 v15, vcc, 0, v13, vcc
	v_add_co_u32_e32 v8, vcc, 0x20000, v12
	global_store_short_d16_hi v[14:15], v9, off offset:352
	s_nop 0
	v_addc_co_u32_e32 v9, vcc, 0, v13, vcc
	global_store_short v[8:9], v10, off offset:352
	v_add_co_u32_e32 v8, vcc, 0x28000, v12
	s_nop 1
	v_addc_co_u32_e32 v9, vcc, 0, v13, vcc
	global_store_short_d16_hi v[8:9], v10, off offset:352
	v_add_co_u32_e32 v8, vcc, 0x30000, v12
	s_nop 1
	v_addc_co_u32_e32 v9, vcc, 0, v13, vcc
	global_store_short v[8:9], v11, off offset:352
	v_add_co_u32_e32 v8, vcc, 0x38000, v12
	s_nop 1
	v_addc_co_u32_e32 v9, vcc, 0, v13, vcc
	global_store_short_d16_hi v[8:9], v11, off offset:352
